# b1L2
# speedup vs baseline: 1.0059x; 1.0059x over previous
; #define PG8_STAGE(bufoff, gbase, voff) do { _Pragma("unroll") for (int _i = 0; _i < 2; ++_i) \
;         __builtin_amdgcn_global_load_lds((const unsigned*)((const char*)(gbase) + (voff)[_i]), (LAS unsigned*)(lds + (bufoff) + ldsw + _i * 8192), 16, 0, 0); } while (0)
; #define PG8_LDA(dst, b, h) do { _Pragma("unroll") for (int m = 0; m < 4; ++m) _Pragma("unroll") for (int k = 0; k < 2; ++k) dst[m][k] = *(const LAS bf16x8*)(lds + PG8_SA(b, h) + aoff + m * 2048 + k * 1024); } while (0)
; #define PG8_LDB(dst, b, h) do { _Pragma("unroll") for (int n = 0; n < 2; ++n) _Pragma("unroll") for (int k = 0; k < 2; ++k) dst[n][k] = *(const LAS bf16x8*)(lds + PG8_SB(b, h) + boff + n * 2048 + k * 1024); } while (0)
; #define PG8_MMA(ai, bj, At, Bt) do { __builtin_amdgcn_s_setprio(1); _Pragma("unroll") for (int m = 0; m < 4; ++m) _Pragma("unroll") for (int n = 0; n < 2; ++n) _Pragma("unroll") for (int k = 0; k < 2; ++k) \
;         acc[ai][bj][m][n] = __builtin_amdgcn_mfma_f32_16x16x32_bf16(Bt[n][k], At[m][k], acc[ai][bj][m][n], 0, 0, 0); __builtin_amdgcn_s_setprio(0); } while (0)
; #define PG8_WAIT_V(n) asm volatile("s_waitcnt vmcnt(" #n ")" ::: "memory")
; #define PG8_WAIT_L(n) asm volatile("s_waitcnt lgkmcnt(" #n ")" ::: "memory")
; #define PG8_BAR __builtin_amdgcn_s_barrier()
; #define PG8_SCHED __builtin_amdgcn_sched_barrier(0)
; template <class Epi, class Job>
; __device__ __forceinline__ void gemm_phase(LAS unsigned char* lds, const Job& S, const Epi& E) {
;     ...
;             PG8_LDB(B0, 0, 0); PG8_SCHED; PG8_LDA(At, 0, 0); PG8_STAGE(PG8_SA(1, 1), a1 + hstepA, voffA);
;             PG8_WAIT_L(8); PG8_BAR; PG8_WAIT_L(0); PG8_MMA(0, 0, At, B0); PG8_BAR; PG8_SCHED;
;             PG8_LDB(B1, 0, 1); PG8_STAGE(PG8_SB(0, 0), b2, voffB);
;             PG8_BAR; PG8_WAIT_L(0); PG8_MMA(0, 1, At, B1); PG8_BAR;
;             PG8_LDA(At, 0, 1); PG8_STAGE(PG8_SA(0, 0), a2, voffA);
;             PG8_BAR; PG8_WAIT_L(0); PG8_MMA(1, 0, At, B0); PG8_BAR; PG8_SCHED;
;             PG8_STAGE(PG8_SB(0, 1), b2 + hstepB, voffB);
;             PG8_WAIT_V(6); PG8_BAR; PG8_MMA(1, 1, At, B1); PG8_BAR;
.LBB0_186:
	s_add_i32 m0, s52, 0xc000
	s_nop 0
	global_load_lds_dwordx4 v144, s[28:29]
	s_add_i32 m0, s52, 0xe000
	s_nop 0
	global_load_lds_dwordx4 v146, s[28:29]
	s_add_u32 s36, s28, 0xfff00080
	s_addc_u32 s37, s29, -1
	s_cmp_eq_u32 s68, 60
	s_cselect_b32 s47, s23, s37
	s_cselect_b32 s46, s22, s36
	s_cselect_b32 s37, s25, s67
	s_cselect_b32 s36, s24, s27
	ds_read_b128 v[190:193], v155 offset:1024
	ds_read_b128 v[198:201], v155 offset:3072
	ds_read_b128 v[206:209], v155 offset:5120
	ds_read_b128 v[214:217], v155 offset:7168
	s_waitcnt lgkmcnt(8)
	s_waitcnt lgkmcnt(0)
	s_setprio 1
	s_barrier
	v_mfma_f32_16x16x32_bf16 v[124:127], v[158:161], v[186:189], v[124:127]
	v_mfma_f32_16x16x32_bf16 v[120:123], v[178:181], v[186:189], v[120:123]
	v_mfma_f32_16x16x32_bf16 v[112:115], v[158:161], v[194:197], v[112:115]
	v_mfma_f32_16x16x32_bf16 v[104:107], v[178:181], v[194:197], v[104:107]
	v_mfma_f32_16x16x32_bf16 v[100:103], v[158:161], v[202:205], v[100:103]
	v_mfma_f32_16x16x32_bf16 v[92:95], v[178:181], v[202:205], v[92:95]
	v_mfma_f32_16x16x32_bf16 v[84:87], v[158:161], v[210:213], v[84:87]
	v_mfma_f32_16x16x32_bf16 v[76:79], v[178:181], v[210:213], v[76:79]
	v_mfma_f32_16x16x32_bf16 v[124:127], v[174:177], v[190:193], v[124:127]
	v_mfma_f32_16x16x32_bf16 v[120:123], v[182:185], v[190:193], v[120:123]
	v_mfma_f32_16x16x32_bf16 v[112:115], v[174:177], v[198:201], v[112:115]
	v_mfma_f32_16x16x32_bf16 v[104:107], v[182:185], v[198:201], v[104:107]
	v_mfma_f32_16x16x32_bf16 v[100:103], v[174:177], v[206:209], v[100:103]
	v_mfma_f32_16x16x32_bf16 v[92:95], v[182:185], v[206:209], v[92:95]
	v_mfma_f32_16x16x32_bf16 v[84:87], v[174:177], v[214:217], v[84:87]
	v_mfma_f32_16x16x32_bf16 v[76:79], v[182:185], v[214:217], v[76:79]
	s_barrier
	s_setprio 0
	ds_read_b128 v[218:221], v156
	ds_read_b128 v[222:225], v156 offset:1024
	ds_read_b128 v[226:229], v156 offset:2048
	ds_read_b128 v[230:233], v156 offset:3072
	s_add_i32 s69, s60, s49
	s_mov_b32 m0, s69
	s_nop 0
	global_load_lds_dwordx4 v136, s[36:37]
	s_add_i32 m0, s69, 0x2000
	s_nop 0
	global_load_lds_dwordx4 v140, s[36:37]
	s_waitcnt lgkmcnt(0)
	s_setprio 1
	s_barrier
	v_mfma_f32_16x16x32_bf16 v[116:119], v[218:221], v[186:189], v[116:119]
	v_mfma_f32_16x16x32_bf16 v[108:111], v[226:229], v[186:189], v[108:111]
	v_mfma_f32_16x16x32_bf16 v[96:99], v[218:221], v[194:197], v[96:99]
	v_mfma_f32_16x16x32_bf16 v[88:91], v[226:229], v[194:197], v[88:91]
	v_mfma_f32_16x16x32_bf16 v[80:83], v[218:221], v[202:205], v[80:83]
	v_mfma_f32_16x16x32_bf16 v[72:75], v[226:229], v[202:205], v[72:75]
	v_mfma_f32_16x16x32_bf16 v[68:71], v[218:221], v[210:213], v[68:71]
	v_mfma_f32_16x16x32_bf16 v[64:67], v[226:229], v[210:213], v[64:67]
	v_mfma_f32_16x16x32_bf16 v[116:119], v[222:225], v[190:193], v[116:119]
	ds_read_b128 v[186:189], v155 offset:16384
	v_mfma_f32_16x16x32_bf16 v[108:111], v[230:233], v[190:193], v[108:111]
	v_mfma_f32_16x16x32_bf16 v[96:99], v[222:225], v[198:201], v[96:99]
	ds_read_b128 v[194:197], v155 offset:18432
	v_mfma_f32_16x16x32_bf16 v[88:91], v[230:233], v[198:201], v[88:91]
	v_mfma_f32_16x16x32_bf16 v[80:83], v[222:225], v[206:209], v[80:83]
	ds_read_b128 v[202:205], v155 offset:20480
	v_mfma_f32_16x16x32_bf16 v[72:75], v[230:233], v[206:209], v[72:75]
	v_mfma_f32_16x16x32_bf16 v[68:71], v[222:225], v[214:217], v[68:71]
	ds_read_b128 v[210:213], v155 offset:22528
	v_mfma_f32_16x16x32_bf16 v[64:67], v[230:233], v[214:217], v[64:67]
	s_barrier
	s_setprio 0
	s_mov_b32 m0, s52
	s_mov_b64 s[100:101], s[46:47]
	global_load_lds_dwordx4 v134, s[46:47]
	s_mov_b32 m0, s53
	s_nop 0
	global_load_lds_dwordx4 v138, s[46:47]
	ds_read_b128 v[190:193], v155 offset:17408
	ds_read_b128 v[198:201], v155 offset:19456
	ds_read_b128 v[206:209], v155 offset:21504
	ds_read_b128 v[214:217], v155 offset:23552
	s_waitcnt vmcnt(8)
	s_waitcnt lgkmcnt(0)
	s_setprio 1
	s_barrier
	v_mfma_f32_16x16x32_bf16 v[60:63], v[158:161], v[186:189], v[60:63]
	v_mfma_f32_16x16x32_bf16 v[56:59], v[178:181], v[186:189], v[56:59]
	v_mfma_f32_16x16x32_bf16 v[52:55], v[158:161], v[194:197], v[52:55]
	v_mfma_f32_16x16x32_bf16 v[44:47], v[178:181], v[194:197], v[44:47]
	v_mfma_f32_16x16x32_bf16 v[36:39], v[158:161], v[202:205], v[36:39]
	v_mfma_f32_16x16x32_bf16 v[28:31], v[178:181], v[202:205], v[28:31]
	v_mfma_f32_16x16x32_bf16 v[20:23], v[158:161], v[210:213], v[20:23]
	v_mfma_f32_16x16x32_bf16 v[12:15], v[178:181], v[210:213], v[12:15]
	v_mfma_f32_16x16x32_bf16 v[60:63], v[174:177], v[190:193], v[60:63]
	v_mfma_f32_16x16x32_bf16 v[56:59], v[182:185], v[190:193], v[56:59]
	v_mfma_f32_16x16x32_bf16 v[52:55], v[174:177], v[198:201], v[52:55]
	v_mfma_f32_16x16x32_bf16 v[44:47], v[182:185], v[198:201], v[44:47]
	v_mfma_f32_16x16x32_bf16 v[36:39], v[174:177], v[206:209], v[36:39]
	v_mfma_f32_16x16x32_bf16 v[28:31], v[182:185], v[206:209], v[28:31]
	v_mfma_f32_16x16x32_bf16 v[20:23], v[174:177], v[214:217], v[20:23]
	v_mfma_f32_16x16x32_bf16 v[12:15], v[182:185], v[214:217], v[12:15]
	s_barrier
	s_setprio 0
	s_add_u32 s70, s36, 0x100000
	s_addc_u32 s71, s37, 0
	s_add_i32 s69, s61, s49
	s_mov_b32 m0, s69
	s_nop 0
	global_load_lds_dwordx4 v136, s[70:71]
	s_add_i32 m0, s69, 0x2000
	s_nop 0
	global_load_lds_dwordx4 v140, s[70:71]
	s_waitcnt vmcnt(6)
	s_setprio 1
	v_add_u32_e32 v157, 0x18000, v153
	s_barrier
; #define PG8_STAGE(bufoff, gbase, voff) do { _Pragma("unroll") for (int _i = 0; _i < 2; ++_i) \
;         __builtin_amdgcn_global_load_lds((const unsigned*)((const char*)(gbase) + (voff)[_i]), (LAS unsigned*)(lds + (bufoff) + ldsw + _i * 8192), 16, 0, 0); } while (0)
; #define PG8_LDA(dst, b, h) do { _Pragma("unroll") for (int m = 0; m < 4; ++m) _Pragma("unroll") for (int k = 0; k < 2; ++k) dst[m][k] = *(const LAS bf16x8*)(lds + PG8_SA(b, h) + aoff + m * 2048 + k * 1024); } while (0)
; #define PG8_LDB(dst, b, h) do { _Pragma("unroll") for (int n = 0; n < 2; ++n) _Pragma("unroll") for (int k = 0; k < 2; ++k) dst[n][k] = *(const LAS bf16x8*)(lds + PG8_SB(b, h) + boff + n * 2048 + k * 1024); } while (0)
; #define PG8_MMA(ai, bj, At, Bt) do { __builtin_amdgcn_s_setprio(1); _Pragma("unroll") for (int m = 0; m < 4; ++m) _Pragma("unroll") for (int n = 0; n < 2; ++n) _Pragma("unroll") for (int k = 0; k < 2; ++k) \
;         acc[ai][bj][m][n] = __builtin_amdgcn_mfma_f32_16x16x32_bf16(Bt[n][k], At[m][k], acc[ai][bj][m][n], 0, 0, 0); __builtin_amdgcn_s_setprio(0); } while (0)
; #define PG8_WAIT_V(n) asm volatile("s_waitcnt vmcnt(" #n ")" ::: "memory")
; #define PG8_WAIT_L(n) asm volatile("s_waitcnt lgkmcnt(" #n ")" ::: "memory")
; #define PG8_BAR __builtin_amdgcn_s_barrier()
; #define PG8_SCHED __builtin_amdgcn_sched_barrier(0)
; template <class Epi, class Job>
; __device__ __forceinline__ void gemm_phase(LAS unsigned char* lds, const Job& S, const Epi& E) {
;     ...
;             PG8_WAIT_V(6); PG8_BAR; PG8_MMA(1, 1, At, B1); PG8_BAR;
;             PG8_LDB(B0, 1, 0); PG8_SCHED; PG8_LDA(At, 1, 0); PG8_STAGE(PG8_SA(0, 1), a2 + hstepA, voffA);
;             PG8_WAIT_L(8); PG8_BAR; PG8_WAIT_L(0); PG8_MMA(0, 0, At, B0); PG8_BAR; PG8_SCHED;
;             PG8_LDB(B1, 1, 1); PG8_STAGE(PG8_SB(1, 0), b3, voffB);
;             PG8_BAR; PG8_WAIT_L(0); PG8_MMA(0, 1, At, B1); PG8_BAR;
;             PG8_LDA(At, 1, 1); PG8_STAGE(PG8_SA(1, 0), a3, voffA);
	v_mfma_f32_16x16x32_bf16 v[48:51], v[218:221], v[186:189], v[48:51]
	ds_read_b128 v[158:161], v157
	v_mfma_f32_16x16x32_bf16 v[40:43], v[226:229], v[186:189], v[40:43]
	v_mfma_f32_16x16x32_bf16 v[32:35], v[218:221], v[194:197], v[32:35]
	ds_read_b128 v[174:177], v157 offset:1024
	v_mfma_f32_16x16x32_bf16 v[24:27], v[226:229], v[194:197], v[24:27]
	v_mfma_f32_16x16x32_bf16 v[16:19], v[218:221], v[202:205], v[16:19]
	ds_read_b128 v[178:181], v157 offset:2048
	v_mfma_f32_16x16x32_bf16 v[8:11], v[226:229], v[202:205], v[8:11]
	v_mfma_f32_16x16x32_bf16 v[4:7], v[218:221], v[210:213], v[4:7]
	ds_read_b128 v[182:185], v157 offset:3072
	v_mfma_f32_16x16x32_bf16 v[0:3], v[226:229], v[210:213], v[0:3]
	v_mfma_f32_16x16x32_bf16 v[48:51], v[222:225], v[190:193], v[48:51]
	ds_read_b128 v[186:189], v155 offset:32768
	v_mfma_f32_16x16x32_bf16 v[40:43], v[230:233], v[190:193], v[40:43]
	v_mfma_f32_16x16x32_bf16 v[32:35], v[222:225], v[198:201], v[32:35]
	ds_read_b128 v[194:197], v155 offset:34816
	v_mfma_f32_16x16x32_bf16 v[24:27], v[230:233], v[198:201], v[24:27]
	v_mfma_f32_16x16x32_bf16 v[16:19], v[222:225], v[206:209], v[16:19]
	ds_read_b128 v[202:205], v155 offset:36864
	v_mfma_f32_16x16x32_bf16 v[8:11], v[230:233], v[206:209], v[8:11]
	v_mfma_f32_16x16x32_bf16 v[4:7], v[222:225], v[214:217], v[4:7]
	ds_read_b128 v[210:213], v155 offset:38912
	v_mfma_f32_16x16x32_bf16 v[0:3], v[230:233], v[214:217], v[0:3]
	s_barrier
	s_setprio 0
	s_add_i32 s69, 0, 0x18000
	v_add_u32_e32 v157, s69, v153
	s_add_u32 s46, s46, 0x100000
	s_addc_u32 s47, s47, 0
	s_mov_b32 m0, s54
	s_nop 0
	global_load_lds_dwordx4 v134, s[46:47]
	s_mov_b32 m0, s55
	s_nop 0
	global_load_lds_dwordx4 v138, s[46:47]
	ds_read_b128 v[190:193], v155 offset:33792
	ds_read_b128 v[198:201], v155 offset:35840
	ds_read_b128 v[206:209], v155 offset:37888
	ds_read_b128 v[214:217], v155 offset:39936
	s_waitcnt lgkmcnt(8)
	s_waitcnt lgkmcnt(0)
	s_setprio 1
	v_add_u32_e32 v157, 0x1c000, v153
	s_barrier
	v_mfma_f32_16x16x32_bf16 v[124:127], v[158:161], v[186:189], v[124:127]
	v_mfma_f32_16x16x32_bf16 v[120:123], v[178:181], v[186:189], v[120:123]
	v_mfma_f32_16x16x32_bf16 v[112:115], v[158:161], v[194:197], v[112:115]
	v_mfma_f32_16x16x32_bf16 v[104:107], v[178:181], v[194:197], v[104:107]
	v_mfma_f32_16x16x32_bf16 v[100:103], v[158:161], v[202:205], v[100:103]
	v_mfma_f32_16x16x32_bf16 v[92:95], v[178:181], v[202:205], v[92:95]
	v_mfma_f32_16x16x32_bf16 v[84:87], v[158:161], v[210:213], v[84:87]
	v_mfma_f32_16x16x32_bf16 v[76:79], v[178:181], v[210:213], v[76:79]
	v_mfma_f32_16x16x32_bf16 v[124:127], v[174:177], v[190:193], v[124:127]
	v_mfma_f32_16x16x32_bf16 v[120:123], v[182:185], v[190:193], v[120:123]
	v_mfma_f32_16x16x32_bf16 v[112:115], v[174:177], v[198:201], v[112:115]
	v_mfma_f32_16x16x32_bf16 v[104:107], v[182:185], v[198:201], v[104:107]
	v_mfma_f32_16x16x32_bf16 v[100:103], v[174:177], v[206:209], v[100:103]
	v_mfma_f32_16x16x32_bf16 v[92:95], v[182:185], v[206:209], v[92:95]
	v_mfma_f32_16x16x32_bf16 v[84:87], v[174:177], v[214:217], v[84:87]
	v_mfma_f32_16x16x32_bf16 v[76:79], v[182:185], v[214:217], v[76:79]
	s_barrier
	s_setprio 0
	ds_read_b128 v[218:221], v157
	ds_read_b128 v[222:225], v157 offset:1024
	ds_read_b128 v[226:229], v157 offset:2048
	ds_read_b128 v[230:233], v157 offset:3072
	s_add_i32 s46, 0, 0x1c000
	s_add_i32 s47, s69, s49
	v_add_u32_e32 v157, s46, v153
	s_add_u32 s98, s36, s10
	s_addc_u32 s99, s37, s11
	s_mov_b32 m0, s47
	s_nop 0
	global_load_lds_dwordx4 v136, s[98:99]
	s_add_i32 m0, s47, 0x2000
	s_nop 0
	global_load_lds_dwordx4 v140, s[98:99]
	s_waitcnt lgkmcnt(0)
	s_setprio 1
	s_barrier
	v_mfma_f32_16x16x32_bf16 v[116:119], v[218:221], v[186:189], v[116:119]
	v_mfma_f32_16x16x32_bf16 v[108:111], v[226:229], v[186:189], v[108:111]
	v_mfma_f32_16x16x32_bf16 v[96:99], v[218:221], v[194:197], v[96:99]
	v_mfma_f32_16x16x32_bf16 v[88:91], v[226:229], v[194:197], v[88:91]
	v_mfma_f32_16x16x32_bf16 v[80:83], v[218:221], v[202:205], v[80:83]
	v_mfma_f32_16x16x32_bf16 v[72:75], v[226:229], v[202:205], v[72:75]
	v_mfma_f32_16x16x32_bf16 v[68:71], v[218:221], v[210:213], v[68:71]
	v_mfma_f32_16x16x32_bf16 v[64:67], v[226:229], v[210:213], v[64:67]
	v_mfma_f32_16x16x32_bf16 v[116:119], v[222:225], v[190:193], v[116:119]
	ds_read_b128 v[186:189], v155 offset:49152
	v_mfma_f32_16x16x32_bf16 v[108:111], v[230:233], v[190:193], v[108:111]
	v_mfma_f32_16x16x32_bf16 v[96:99], v[222:225], v[198:201], v[96:99]
	ds_read_b128 v[194:197], v155 offset:51200
	v_mfma_f32_16x16x32_bf16 v[88:91], v[230:233], v[198:201], v[88:91]
	v_mfma_f32_16x16x32_bf16 v[80:83], v[222:225], v[206:209], v[80:83]
	ds_read_b128 v[202:205], v155 offset:53248
	v_mfma_f32_16x16x32_bf16 v[72:75], v[230:233], v[206:209], v[72:75]
	v_mfma_f32_16x16x32_bf16 v[68:71], v[222:225], v[214:217], v[68:71]
	ds_read_b128 v[210:213], v155 offset:55296
	v_mfma_f32_16x16x32_bf16 v[64:67], v[230:233], v[214:217], v[64:67]
	s_barrier
; #define PG8_STAGE(bufoff, gbase, voff) do { _Pragma("unroll") for (int _i = 0; _i < 2; ++_i) \
;         __builtin_amdgcn_global_load_lds((const unsigned*)((const char*)(gbase) + (voff)[_i]), (LAS unsigned*)(lds + (bufoff) + ldsw + _i * 8192), 16, 0, 0); } while (0)
; #define PG8_LDA(dst, b, h) do { _Pragma("unroll") for (int m = 0; m < 4; ++m) _Pragma("unroll") for (int k = 0; k < 2; ++k) dst[m][k] = *(const LAS bf16x8*)(lds + PG8_SA(b, h) + aoff + m * 2048 + k * 1024); } while (0)
; #define PG8_MMA(ai, bj, At, Bt) do { __builtin_amdgcn_s_setprio(1); _Pragma("unroll") for (int m = 0; m < 4; ++m) _Pragma("unroll") for (int n = 0; n < 2; ++n) _Pragma("unroll") for (int k = 0; k < 2; ++k) \
;         acc[ai][bj][m][n] = __builtin_amdgcn_mfma_f32_16x16x32_bf16(Bt[n][k], At[m][k], acc[ai][bj][m][n], 0, 0, 0); __builtin_amdgcn_s_setprio(0); } while (0)
; #define PG8_WAIT_V(n) asm volatile("s_waitcnt vmcnt(" #n ")" ::: "memory")
; #define PG8_WAIT_L(n) asm volatile("s_waitcnt lgkmcnt(" #n ")" ::: "memory")
; #define PG8_BAR __builtin_amdgcn_s_barrier()
; #define PG8_SCHED __builtin_amdgcn_sched_barrier(0)
;     __device__ __forceinline__ void operator()(const f32x4 (&acc)[2][2][4][2], const Unit& u, int wr, int wc, int fr, int fq) const {
;         const int row0 = u.orow + wr * 64 + fr;
;         bf16_t* base; size_t rstride, bjstride;
;         if (u.ocol < 6144) { const int sect = u.ocol >> 11, hh0 = (u.ocol & 2047) >> 7, b = u.orow >= SEQ ? 1 : 0;
;             base = qkv + (size_t)sect * MTOK * 2048 + ((size_t)(b * 16 + hh0) * SEQ + (row0 & (SEQ - 1))) * 128 + wc * 32 + 8 * fq; rstride = 128; bjstride = (size_t)SEQ * 128; }
;         else { base = proj2 + (size_t)row0 * NP2 + (u.ocol - 6144) + wc * 32 + 8 * fq; rstride = NP2; bjstride = HALF; }
; template <class Epi, class Job>
; __device__ __forceinline__ void gemm_phase(LAS unsigned char* lds, const Job& S, const Epi& E) {
;     ...
;             PG8_LDA(At, 1, 1); PG8_STAGE(PG8_SA(1, 0), a3, voffA);
;             PG8_BAR; PG8_WAIT_L(0); PG8_MMA(1, 0, At, B0); PG8_BAR; PG8_SCHED;
;             PG8_STAGE(PG8_SB(1, 1), b3 + hstepB, voffB);
;             PG8_WAIT_V(6); PG8_BAR; PG8_MMA(1, 1, At, B1); PG8_BAR;
;         }
;         E(acc, cur, wr, wc, fr, fq);
	s_setprio 0
	s_mov_b32 m0, s56
	s_add_u32 s100, s100, s10
	s_addc_u32 s101, s101, s11
	global_load_lds_dwordx4 v134, s[100:101]
	s_mov_b32 m0, s57
	s_nop 0
	global_load_lds_dwordx4 v138, s[100:101]
	ds_read_b128 v[190:193], v155 offset:50176
	ds_read_b128 v[198:201], v155 offset:52224
	ds_read_b128 v[206:209], v155 offset:54272
	ds_read_b128 v[214:217], v155 offset:56320
	s_waitcnt vmcnt(8)
	s_waitcnt lgkmcnt(0)
	s_setprio 1
	s_barrier
	v_mfma_f32_16x16x32_bf16 v[60:63], v[158:161], v[186:189], v[60:63]
	v_mfma_f32_16x16x32_bf16 v[56:59], v[178:181], v[186:189], v[56:59]
	v_mfma_f32_16x16x32_bf16 v[52:55], v[158:161], v[194:197], v[52:55]
	v_mfma_f32_16x16x32_bf16 v[44:47], v[178:181], v[194:197], v[44:47]
	v_mfma_f32_16x16x32_bf16 v[36:39], v[158:161], v[202:205], v[36:39]
	v_mfma_f32_16x16x32_bf16 v[28:31], v[178:181], v[202:205], v[28:31]
	v_mfma_f32_16x16x32_bf16 v[20:23], v[158:161], v[210:213], v[20:23]
	v_mfma_f32_16x16x32_bf16 v[12:15], v[178:181], v[210:213], v[12:15]
	v_mfma_f32_16x16x32_bf16 v[60:63], v[174:177], v[190:193], v[60:63]
	v_mfma_f32_16x16x32_bf16 v[56:59], v[182:185], v[190:193], v[56:59]
	v_mfma_f32_16x16x32_bf16 v[52:55], v[174:177], v[198:201], v[52:55]
	v_mfma_f32_16x16x32_bf16 v[44:47], v[182:185], v[198:201], v[44:47]
	v_mfma_f32_16x16x32_bf16 v[36:39], v[174:177], v[206:209], v[36:39]
	v_mfma_f32_16x16x32_bf16 v[28:31], v[182:185], v[206:209], v[28:31]
	v_mfma_f32_16x16x32_bf16 v[20:23], v[174:177], v[214:217], v[20:23]
	v_mfma_f32_16x16x32_bf16 v[12:15], v[182:185], v[214:217], v[12:15]
	s_barrier
	s_setprio 0
	s_add_u32 s36, s36, 0x100080
	s_addc_u32 s37, s37, 0
	s_add_i32 s46, s46, s49
	s_mov_b32 m0, s46
	s_nop 0
	global_load_lds_dwordx4 v136, s[36:37]
	s_add_i32 m0, s46, 0x2000
	s_nop 0
	global_load_lds_dwordx4 v140, s[36:37]
	s_waitcnt vmcnt(6)
	s_setprio 1
	s_barrier
	v_mfma_f32_16x16x32_bf16 v[48:51], v[218:221], v[186:189], v[48:51]
	ds_read_b128 v[158:161], v154
	v_mfma_f32_16x16x32_bf16 v[40:43], v[226:229], v[186:189], v[40:43]
	v_mfma_f32_16x16x32_bf16 v[32:35], v[218:221], v[194:197], v[32:35]
	ds_read_b128 v[174:177], v154 offset:1024
	v_mfma_f32_16x16x32_bf16 v[24:27], v[226:229], v[194:197], v[24:27]
	v_mfma_f32_16x16x32_bf16 v[16:19], v[218:221], v[202:205], v[16:19]
	ds_read_b128 v[178:181], v154 offset:2048
	v_mfma_f32_16x16x32_bf16 v[8:11], v[226:229], v[202:205], v[8:11]
	v_mfma_f32_16x16x32_bf16 v[4:7], v[218:221], v[210:213], v[4:7]
	ds_read_b128 v[182:185], v154 offset:3072
	v_mfma_f32_16x16x32_bf16 v[0:3], v[226:229], v[210:213], v[0:3]
	v_mfma_f32_16x16x32_bf16 v[48:51], v[222:225], v[190:193], v[48:51]
	ds_read_b128 v[186:189], v155
	v_mfma_f32_16x16x32_bf16 v[40:43], v[230:233], v[190:193], v[40:43]
	v_mfma_f32_16x16x32_bf16 v[32:35], v[222:225], v[198:201], v[32:35]
	ds_read_b128 v[194:197], v155 offset:2048
	v_mfma_f32_16x16x32_bf16 v[24:27], v[230:233], v[198:201], v[24:27]
	v_mfma_f32_16x16x32_bf16 v[16:19], v[222:225], v[206:209], v[16:19]
	ds_read_b128 v[202:205], v155 offset:4096
	v_mfma_f32_16x16x32_bf16 v[8:11], v[230:233], v[206:209], v[8:11]
	v_mfma_f32_16x16x32_bf16 v[4:7], v[222:225], v[214:217], v[4:7]
	ds_read_b128 v[210:213], v155 offset:6144
	v_mfma_f32_16x16x32_bf16 v[0:3], v[230:233], v[214:217], v[0:3]
	s_barrier
	s_setprio 0
	s_add_i32 s68, s68, 2
	s_add_u32 s28, s28, 0x100
	s_addc_u32 s29, s29, 0
	s_add_u32 s27, s27, 0x100
	s_addc_u32 s67, s67, 0
	s_cmp_gt_u32 s68, 61
	s_cbranch_scc0 .LBB0_186
	s_waitcnt lgkmcnt(0)
	v_add_u32_e32 v157, s66, v131
	s_cmpk_gt_i32 s26, 0x17ff
	s_mov_b64 s[28:29], -1
	s_cbranch_scc0 .LBB0_189
	v_mov_b64_e32 v[150:151], s[20:21]
	v_mad_i64_i32 v[150:151], s[28:29], v157, s62, v[150:151]
	s_mov_b32 s27, s9
	v_lshl_add_u64 v[150:151], s[26:27], 1, v[150:151]
	v_lshl_add_u64 v[150:151], v[150:151], 0, s[12:13]
	s_mov_b64 s[28:29], 0

; #define PG8_STAGE(bufoff, gbase, voff) do { _Pragma("unroll") for (int _i = 0; _i < 2; ++_i) \
;         __builtin_amdgcn_global_load_lds((const unsigned*)((const char*)(gbase) + (voff)[_i]), (LAS unsigned*)(lds + (bufoff) + ldsw + _i * 8192), 16, 0, 0); } while (0)
; #define PG8_LDA(dst, b, h) do { _Pragma("unroll") for (int m = 0; m < 4; ++m) _Pragma("unroll") for (int k = 0; k < 2; ++k) dst[m][k] = *(const LAS bf16x8*)(lds + PG8_SA(b, h) + aoff + m * 2048 + k * 1024); } while (0)
; #define PG8_LDB(dst, b, h) do { _Pragma("unroll") for (int n = 0; n < 2; ++n) _Pragma("unroll") for (int k = 0; k < 2; ++k) dst[n][k] = *(const LAS bf16x8*)(lds + PG8_SB(b, h) + boff + n * 2048 + k * 1024); } while (0)
; #define PG8_MMA(ai, bj, At, Bt) do { __builtin_amdgcn_s_setprio(1); _Pragma("unroll") for (int m = 0; m < 4; ++m) _Pragma("unroll") for (int n = 0; n < 2; ++n) _Pragma("unroll") for (int k = 0; k < 2; ++k) \
;         acc[ai][bj][m][n] = __builtin_amdgcn_mfma_f32_16x16x32_bf16(Bt[n][k], At[m][k], acc[ai][bj][m][n], 0, 0, 0); __builtin_amdgcn_s_setprio(0); } while (0)
; #define PG8_WAIT_V(n) asm volatile("s_waitcnt vmcnt(" #n ")" ::: "memory")
; #define PG8_WAIT_L(n) asm volatile("s_waitcnt lgkmcnt(" #n ")" ::: "memory")
; #define PG8_BAR __builtin_amdgcn_s_barrier()
; #define PG8_SCHED __builtin_amdgcn_sched_barrier(0)
; template <class Epi, class Job>
; __device__ __forceinline__ void gemm_phase(LAS unsigned char* lds, const Job& S, const Epi& E) {
;     ...
;             PG8_LDB(B0, 0, 0); PG8_SCHED; PG8_LDA(At, 0, 0); PG8_STAGE(PG8_SA(1, 1), a1 + hstepA, voffA);
;             PG8_WAIT_L(8); PG8_BAR; PG8_WAIT_L(0); PG8_MMA(0, 0, At, B0); PG8_BAR; PG8_SCHED;
;             PG8_LDB(B1, 0, 1); PG8_STAGE(PG8_SB(0, 0), b2, voffB);
;             PG8_BAR; PG8_WAIT_L(0); PG8_MMA(0, 1, At, B1); PG8_BAR;
;             PG8_LDA(At, 0, 1); PG8_STAGE(PG8_SA(0, 0), a2, voffA);
;             PG8_BAR; PG8_WAIT_L(0); PG8_MMA(1, 0, At, B0); PG8_BAR; PG8_SCHED;
;             PG8_STAGE(PG8_SB(0, 1), b2 + hstepB, voffB);
;             PG8_WAIT_V(6); PG8_BAR; PG8_MMA(1, 1, At, B1); PG8_BAR;
.LBB0_457:
	s_add_i32 m0, s57, 0xc000
	s_nop 0
	global_load_lds_dwordx4 v132, s[36:37]
	s_add_i32 m0, s57, 0xe000
	s_nop 0
	global_load_lds_dwordx4 v142, s[36:37]
	s_add_u32 s46, s36, 0xfff00080
	s_addc_u32 s47, s37, -1
	s_cmp_eq_u32 s81, 60
	s_cselect_b32 s49, s29, s47
	s_cselect_b32 s48, s28, s46
	s_cselect_b32 s47, s31, s80
	s_cselect_b32 s46, s30, s79
	ds_read_b128 v[174:177], v151 offset:1024
	ds_read_b128 v[182:185], v151 offset:3072
	ds_read_b128 v[190:193], v151 offset:5120
	ds_read_b128 v[198:201], v151 offset:7168
	s_waitcnt lgkmcnt(8)
	s_waitcnt lgkmcnt(0)
	s_setprio 1
	s_barrier
	v_mfma_f32_16x16x32_bf16 v[124:127], v[154:157], v[170:173], v[124:127]
	v_mfma_f32_16x16x32_bf16 v[120:123], v[162:165], v[170:173], v[120:123]
	v_mfma_f32_16x16x32_bf16 v[116:119], v[154:157], v[178:181], v[116:119]
	v_mfma_f32_16x16x32_bf16 v[108:111], v[162:165], v[178:181], v[108:111]
	v_mfma_f32_16x16x32_bf16 v[100:103], v[154:157], v[186:189], v[100:103]
	v_mfma_f32_16x16x32_bf16 v[92:95], v[162:165], v[186:189], v[92:95]
	v_mfma_f32_16x16x32_bf16 v[84:87], v[154:157], v[194:197], v[84:87]
	v_mfma_f32_16x16x32_bf16 v[76:79], v[162:165], v[194:197], v[76:79]
	v_mfma_f32_16x16x32_bf16 v[124:127], v[158:161], v[174:177], v[124:127]
	v_mfma_f32_16x16x32_bf16 v[120:123], v[166:169], v[174:177], v[120:123]
	v_mfma_f32_16x16x32_bf16 v[116:119], v[158:161], v[182:185], v[116:119]
	v_mfma_f32_16x16x32_bf16 v[108:111], v[166:169], v[182:185], v[108:111]
	v_mfma_f32_16x16x32_bf16 v[100:103], v[158:161], v[190:193], v[100:103]
	v_mfma_f32_16x16x32_bf16 v[92:95], v[166:169], v[190:193], v[92:95]
	v_mfma_f32_16x16x32_bf16 v[84:87], v[158:161], v[198:201], v[84:87]
	v_mfma_f32_16x16x32_bf16 v[76:79], v[166:169], v[198:201], v[76:79]
	s_barrier
	s_setprio 0
	ds_read_b128 v[202:205], v152
	ds_read_b128 v[206:209], v152 offset:1024
	ds_read_b128 v[210:213], v152 offset:2048
	ds_read_b128 v[214:217], v152 offset:3072
	s_add_i32 s82, s66, s56
	s_mov_b32 m0, s82
	s_nop 0
	global_load_lds_dwordx4 v136, s[46:47]
	s_add_i32 m0, s82, 0x2000
	s_nop 0
	global_load_lds_dwordx4 v140, s[46:47]
	s_waitcnt lgkmcnt(0)
	s_setprio 1
	s_barrier
	v_mfma_f32_16x16x32_bf16 v[112:115], v[202:205], v[170:173], v[112:115]
	v_mfma_f32_16x16x32_bf16 v[104:107], v[210:213], v[170:173], v[104:107]
	v_mfma_f32_16x16x32_bf16 v[96:99], v[202:205], v[178:181], v[96:99]
	v_mfma_f32_16x16x32_bf16 v[88:91], v[210:213], v[178:181], v[88:91]
	v_mfma_f32_16x16x32_bf16 v[80:83], v[202:205], v[186:189], v[80:83]
	v_mfma_f32_16x16x32_bf16 v[72:75], v[210:213], v[186:189], v[72:75]
	v_mfma_f32_16x16x32_bf16 v[68:71], v[202:205], v[194:197], v[68:71]
	v_mfma_f32_16x16x32_bf16 v[64:67], v[210:213], v[194:197], v[64:67]
	v_mfma_f32_16x16x32_bf16 v[112:115], v[206:209], v[174:177], v[112:115]
	ds_read_b128 v[170:173], v151 offset:16384
	v_mfma_f32_16x16x32_bf16 v[104:107], v[214:217], v[174:177], v[104:107]
	v_mfma_f32_16x16x32_bf16 v[96:99], v[206:209], v[182:185], v[96:99]
	ds_read_b128 v[178:181], v151 offset:18432
	v_mfma_f32_16x16x32_bf16 v[88:91], v[214:217], v[182:185], v[88:91]
	v_mfma_f32_16x16x32_bf16 v[80:83], v[206:209], v[190:193], v[80:83]
	ds_read_b128 v[186:189], v151 offset:20480
	v_mfma_f32_16x16x32_bf16 v[72:75], v[214:217], v[190:193], v[72:75]
	v_mfma_f32_16x16x32_bf16 v[68:71], v[206:209], v[198:201], v[68:71]
	ds_read_b128 v[194:197], v151 offset:22528
	v_mfma_f32_16x16x32_bf16 v[64:67], v[214:217], v[198:201], v[64:67]
	s_barrier
	s_setprio 0
	s_mov_b32 m0, s57
	s_mov_b64 s[100:101], s[48:49]
	global_load_lds_dwordx4 v134, s[48:49]
	s_mov_b32 m0, s58
	s_nop 0
	global_load_lds_dwordx4 v138, s[48:49]
	ds_read_b128 v[174:177], v151 offset:17408
	ds_read_b128 v[182:185], v151 offset:19456
	ds_read_b128 v[190:193], v151 offset:21504
	ds_read_b128 v[198:201], v151 offset:23552
	s_waitcnt vmcnt(8)
	s_waitcnt lgkmcnt(0)
	s_setprio 1
	s_barrier
	v_mfma_f32_16x16x32_bf16 v[60:63], v[154:157], v[170:173], v[60:63]
	v_mfma_f32_16x16x32_bf16 v[56:59], v[162:165], v[170:173], v[56:59]
	v_mfma_f32_16x16x32_bf16 v[52:55], v[154:157], v[178:181], v[52:55]
	v_mfma_f32_16x16x32_bf16 v[44:47], v[162:165], v[178:181], v[44:47]
	v_mfma_f32_16x16x32_bf16 v[36:39], v[154:157], v[186:189], v[36:39]
	v_mfma_f32_16x16x32_bf16 v[28:31], v[162:165], v[186:189], v[28:31]
	v_mfma_f32_16x16x32_bf16 v[20:23], v[154:157], v[194:197], v[20:23]
	v_mfma_f32_16x16x32_bf16 v[12:15], v[162:165], v[194:197], v[12:15]
	v_mfma_f32_16x16x32_bf16 v[60:63], v[158:161], v[174:177], v[60:63]
	v_mfma_f32_16x16x32_bf16 v[56:59], v[166:169], v[174:177], v[56:59]
	v_mfma_f32_16x16x32_bf16 v[52:55], v[158:161], v[182:185], v[52:55]
	v_mfma_f32_16x16x32_bf16 v[44:47], v[166:169], v[182:185], v[44:47]
	v_mfma_f32_16x16x32_bf16 v[36:39], v[158:161], v[190:193], v[36:39]
	v_mfma_f32_16x16x32_bf16 v[28:31], v[166:169], v[190:193], v[28:31]
	v_mfma_f32_16x16x32_bf16 v[20:23], v[158:161], v[198:201], v[20:23]
	v_mfma_f32_16x16x32_bf16 v[12:15], v[166:169], v[198:201], v[12:15]
	s_barrier
	s_setprio 0
	s_add_u32 s82, s46, 0x100000
	s_addc_u32 s83, s47, 0
	s_add_i32 s84, s67, s56
	s_mov_b32 m0, s84
	s_nop 0
	global_load_lds_dwordx4 v136, s[82:83]
	s_add_i32 m0, s84, 0x2000
	s_nop 0
	global_load_lds_dwordx4 v140, s[82:83]
	s_waitcnt vmcnt(6)
	s_setprio 1
	v_add_u32_e32 v153, 0x18000, v148
	s_barrier
; #define PG8_STAGE(bufoff, gbase, voff) do { _Pragma("unroll") for (int _i = 0; _i < 2; ++_i) \
;         __builtin_amdgcn_global_load_lds((const unsigned*)((const char*)(gbase) + (voff)[_i]), (LAS unsigned*)(lds + (bufoff) + ldsw + _i * 8192), 16, 0, 0); } while (0)
; #define PG8_LDA(dst, b, h) do { _Pragma("unroll") for (int m = 0; m < 4; ++m) _Pragma("unroll") for (int k = 0; k < 2; ++k) dst[m][k] = *(const LAS bf16x8*)(lds + PG8_SA(b, h) + aoff + m * 2048 + k * 1024); } while (0)
; #define PG8_LDB(dst, b, h) do { _Pragma("unroll") for (int n = 0; n < 2; ++n) _Pragma("unroll") for (int k = 0; k < 2; ++k) dst[n][k] = *(const LAS bf16x8*)(lds + PG8_SB(b, h) + boff + n * 2048 + k * 1024); } while (0)
; #define PG8_MMA(ai, bj, At, Bt) do { __builtin_amdgcn_s_setprio(1); _Pragma("unroll") for (int m = 0; m < 4; ++m) _Pragma("unroll") for (int n = 0; n < 2; ++n) _Pragma("unroll") for (int k = 0; k < 2; ++k) \
;         acc[ai][bj][m][n] = __builtin_amdgcn_mfma_f32_16x16x32_bf16(Bt[n][k], At[m][k], acc[ai][bj][m][n], 0, 0, 0); __builtin_amdgcn_s_setprio(0); } while (0)
; #define PG8_WAIT_V(n) asm volatile("s_waitcnt vmcnt(" #n ")" ::: "memory")
; #define PG8_WAIT_L(n) asm volatile("s_waitcnt lgkmcnt(" #n ")" ::: "memory")
; #define PG8_BAR __builtin_amdgcn_s_barrier()
; #define PG8_SCHED __builtin_amdgcn_sched_barrier(0)
; template <class Epi, class Job>
; __device__ __forceinline__ void gemm_phase(LAS unsigned char* lds, const Job& S, const Epi& E) {
;     ...
;             PG8_WAIT_V(6); PG8_BAR; PG8_MMA(1, 1, At, B1); PG8_BAR;
;             PG8_LDB(B0, 1, 0); PG8_SCHED; PG8_LDA(At, 1, 0); PG8_STAGE(PG8_SA(0, 1), a2 + hstepA, voffA);
;             PG8_WAIT_L(8); PG8_BAR; PG8_WAIT_L(0); PG8_MMA(0, 0, At, B0); PG8_BAR; PG8_SCHED;
;             PG8_LDB(B1, 1, 1); PG8_STAGE(PG8_SB(1, 0), b3, voffB);
;             PG8_BAR; PG8_WAIT_L(0); PG8_MMA(0, 1, At, B1); PG8_BAR;
;             PG8_LDA(At, 1, 1); PG8_STAGE(PG8_SA(1, 0), a3, voffA);
	v_mfma_f32_16x16x32_bf16 v[48:51], v[202:205], v[170:173], v[48:51]
	ds_read_b128 v[154:157], v153
	v_mfma_f32_16x16x32_bf16 v[40:43], v[210:213], v[170:173], v[40:43]
	v_mfma_f32_16x16x32_bf16 v[32:35], v[202:205], v[178:181], v[32:35]
	ds_read_b128 v[158:161], v153 offset:1024
	v_mfma_f32_16x16x32_bf16 v[24:27], v[210:213], v[178:181], v[24:27]
	v_mfma_f32_16x16x32_bf16 v[16:19], v[202:205], v[186:189], v[16:19]
	ds_read_b128 v[162:165], v153 offset:2048
	v_mfma_f32_16x16x32_bf16 v[8:11], v[210:213], v[186:189], v[8:11]
	v_mfma_f32_16x16x32_bf16 v[4:7], v[202:205], v[194:197], v[4:7]
	ds_read_b128 v[166:169], v153 offset:3072
	v_mfma_f32_16x16x32_bf16 v[0:3], v[210:213], v[194:197], v[0:3]
	v_mfma_f32_16x16x32_bf16 v[48:51], v[206:209], v[174:177], v[48:51]
	ds_read_b128 v[170:173], v151 offset:32768
	v_mfma_f32_16x16x32_bf16 v[40:43], v[214:217], v[174:177], v[40:43]
	v_mfma_f32_16x16x32_bf16 v[32:35], v[206:209], v[182:185], v[32:35]
	ds_read_b128 v[178:181], v151 offset:34816
	v_mfma_f32_16x16x32_bf16 v[24:27], v[214:217], v[182:185], v[24:27]
	v_mfma_f32_16x16x32_bf16 v[16:19], v[206:209], v[190:193], v[16:19]
	ds_read_b128 v[186:189], v151 offset:36864
	v_mfma_f32_16x16x32_bf16 v[8:11], v[214:217], v[190:193], v[8:11]
	v_mfma_f32_16x16x32_bf16 v[4:7], v[206:209], v[198:201], v[4:7]
	ds_read_b128 v[194:197], v151 offset:38912
	v_mfma_f32_16x16x32_bf16 v[0:3], v[214:217], v[198:201], v[0:3]
	s_barrier
	s_setprio 0
	s_add_i32 s82, 0, 0x18000
	v_add_u32_e32 v153, s82, v148
	s_add_u32 s48, s48, 0x100000
	s_addc_u32 s49, s49, 0
	s_mov_b32 m0, s59
	s_nop 0
	global_load_lds_dwordx4 v134, s[48:49]
	s_mov_b32 m0, s60
	s_nop 0
	global_load_lds_dwordx4 v138, s[48:49]
	ds_read_b128 v[174:177], v151 offset:33792
	ds_read_b128 v[182:185], v151 offset:35840
	ds_read_b128 v[190:193], v151 offset:37888
	ds_read_b128 v[198:201], v151 offset:39936
	s_waitcnt lgkmcnt(8)
	s_waitcnt lgkmcnt(0)
	s_setprio 1
	v_add_u32_e32 v153, 0x1c000, v148
	s_barrier
	v_mfma_f32_16x16x32_bf16 v[124:127], v[154:157], v[170:173], v[124:127]
	v_mfma_f32_16x16x32_bf16 v[120:123], v[162:165], v[170:173], v[120:123]
	v_mfma_f32_16x16x32_bf16 v[116:119], v[154:157], v[178:181], v[116:119]
	v_mfma_f32_16x16x32_bf16 v[108:111], v[162:165], v[178:181], v[108:111]
	v_mfma_f32_16x16x32_bf16 v[100:103], v[154:157], v[186:189], v[100:103]
	v_mfma_f32_16x16x32_bf16 v[92:95], v[162:165], v[186:189], v[92:95]
	v_mfma_f32_16x16x32_bf16 v[84:87], v[154:157], v[194:197], v[84:87]
	v_mfma_f32_16x16x32_bf16 v[76:79], v[162:165], v[194:197], v[76:79]
	v_mfma_f32_16x16x32_bf16 v[124:127], v[158:161], v[174:177], v[124:127]
	v_mfma_f32_16x16x32_bf16 v[120:123], v[166:169], v[174:177], v[120:123]
	v_mfma_f32_16x16x32_bf16 v[116:119], v[158:161], v[182:185], v[116:119]
	v_mfma_f32_16x16x32_bf16 v[108:111], v[166:169], v[182:185], v[108:111]
	v_mfma_f32_16x16x32_bf16 v[100:103], v[158:161], v[190:193], v[100:103]
	v_mfma_f32_16x16x32_bf16 v[92:95], v[166:169], v[190:193], v[92:95]
	v_mfma_f32_16x16x32_bf16 v[84:87], v[158:161], v[198:201], v[84:87]
	v_mfma_f32_16x16x32_bf16 v[76:79], v[166:169], v[198:201], v[76:79]
	s_barrier
	s_setprio 0
	ds_read_b128 v[202:205], v153
	ds_read_b128 v[206:209], v153 offset:1024
	ds_read_b128 v[210:213], v153 offset:2048
	ds_read_b128 v[214:217], v153 offset:3072
	s_add_i32 s48, 0, 0x1c000
	s_add_i32 s49, s82, s56
	v_add_u32_e32 v153, s48, v148
	s_add_u32 s98, s46, s8
	s_addc_u32 s99, s47, s9
	s_mov_b32 m0, s49
	s_nop 0
	global_load_lds_dwordx4 v136, s[98:99]
	s_add_i32 m0, s49, 0x2000
	s_nop 0
	global_load_lds_dwordx4 v140, s[98:99]
	s_waitcnt lgkmcnt(0)
	s_setprio 1
	s_barrier
	v_mfma_f32_16x16x32_bf16 v[112:115], v[202:205], v[170:173], v[112:115]
	v_mfma_f32_16x16x32_bf16 v[104:107], v[210:213], v[170:173], v[104:107]
	v_mfma_f32_16x16x32_bf16 v[96:99], v[202:205], v[178:181], v[96:99]
	v_mfma_f32_16x16x32_bf16 v[88:91], v[210:213], v[178:181], v[88:91]
	v_mfma_f32_16x16x32_bf16 v[80:83], v[202:205], v[186:189], v[80:83]
	v_mfma_f32_16x16x32_bf16 v[72:75], v[210:213], v[186:189], v[72:75]
	v_mfma_f32_16x16x32_bf16 v[68:71], v[202:205], v[194:197], v[68:71]
	v_mfma_f32_16x16x32_bf16 v[64:67], v[210:213], v[194:197], v[64:67]
	v_mfma_f32_16x16x32_bf16 v[112:115], v[206:209], v[174:177], v[112:115]
	ds_read_b128 v[170:173], v151 offset:49152
	v_mfma_f32_16x16x32_bf16 v[104:107], v[214:217], v[174:177], v[104:107]
	v_mfma_f32_16x16x32_bf16 v[96:99], v[206:209], v[182:185], v[96:99]
	ds_read_b128 v[178:181], v151 offset:51200
	v_mfma_f32_16x16x32_bf16 v[88:91], v[214:217], v[182:185], v[88:91]
	v_mfma_f32_16x16x32_bf16 v[80:83], v[206:209], v[190:193], v[80:83]
	ds_read_b128 v[186:189], v151 offset:53248
	v_mfma_f32_16x16x32_bf16 v[72:75], v[214:217], v[190:193], v[72:75]
	v_mfma_f32_16x16x32_bf16 v[68:71], v[206:209], v[198:201], v[68:71]
	ds_read_b128 v[194:197], v151 offset:55296
	v_mfma_f32_16x16x32_bf16 v[64:67], v[214:217], v[198:201], v[64:67]
	s_barrier
	s_setprio 0
	s_mov_b32 m0, s62
	s_add_u32 s100, s100, s8
	s_addc_u32 s101, s101, s9
	global_load_lds_dwordx4 v134, s[100:101]
	s_mov_b32 m0, s63
	s_nop 0
	global_load_lds_dwordx4 v138, s[100:101]
	ds_read_b128 v[174:177], v151 offset:50176
	ds_read_b128 v[182:185], v151 offset:52224
	ds_read_b128 v[190:193], v151 offset:54272
	ds_read_b128 v[198:201], v151 offset:56320
	s_waitcnt vmcnt(8)
	s_waitcnt lgkmcnt(0)
	s_setprio 1
	s_barrier
; #define PG8_STAGE(bufoff, gbase, voff) do { _Pragma("unroll") for (int _i = 0; _i < 2; ++_i) \
;         __builtin_amdgcn_global_load_lds((const unsigned*)((const char*)(gbase) + (voff)[_i]), (LAS unsigned*)(lds + (bufoff) + ldsw + _i * 8192), 16, 0, 0); } while (0)
; #define PG8_MMA(ai, bj, At, Bt) do { __builtin_amdgcn_s_setprio(1); _Pragma("unroll") for (int m = 0; m < 4; ++m) _Pragma("unroll") for (int n = 0; n < 2; ++n) _Pragma("unroll") for (int k = 0; k < 2; ++k) \
;         acc[ai][bj][m][n] = __builtin_amdgcn_mfma_f32_16x16x32_bf16(Bt[n][k], At[m][k], acc[ai][bj][m][n], 0, 0, 0); __builtin_amdgcn_s_setprio(0); } while (0)
; #define PG8_WAIT_V(n) asm volatile("s_waitcnt vmcnt(" #n ")" ::: "memory")
; #define PG8_WAIT_L(n) asm volatile("s_waitcnt lgkmcnt(" #n ")" ::: "memory")
; #define PG8_BAR __builtin_amdgcn_s_barrier()
; #define PG8_SCHED __builtin_amdgcn_sched_barrier(0)
; template <class Epi, class Job>
; __device__ __forceinline__ void gemm_phase(LAS unsigned char* lds, const Job& S, const Epi& E) {
;     ...
;             PG8_BAR; PG8_WAIT_L(0); PG8_MMA(1, 0, At, B0); PG8_BAR; PG8_SCHED;
;             PG8_STAGE(PG8_SB(1, 1), b3 + hstepB, voffB);
;             PG8_WAIT_V(6); PG8_BAR; PG8_MMA(1, 1, At, B1); PG8_BAR;
;         }
	v_mfma_f32_16x16x32_bf16 v[60:63], v[154:157], v[170:173], v[60:63]
	v_mfma_f32_16x16x32_bf16 v[56:59], v[162:165], v[170:173], v[56:59]
	v_mfma_f32_16x16x32_bf16 v[52:55], v[154:157], v[178:181], v[52:55]
	v_mfma_f32_16x16x32_bf16 v[44:47], v[162:165], v[178:181], v[44:47]
	v_mfma_f32_16x16x32_bf16 v[36:39], v[154:157], v[186:189], v[36:39]
	v_mfma_f32_16x16x32_bf16 v[28:31], v[162:165], v[186:189], v[28:31]
	v_mfma_f32_16x16x32_bf16 v[20:23], v[154:157], v[194:197], v[20:23]
	v_mfma_f32_16x16x32_bf16 v[12:15], v[162:165], v[194:197], v[12:15]
	v_mfma_f32_16x16x32_bf16 v[60:63], v[158:161], v[174:177], v[60:63]
	v_mfma_f32_16x16x32_bf16 v[56:59], v[166:169], v[174:177], v[56:59]
	v_mfma_f32_16x16x32_bf16 v[52:55], v[158:161], v[182:185], v[52:55]
	v_mfma_f32_16x16x32_bf16 v[44:47], v[166:169], v[182:185], v[44:47]
	v_mfma_f32_16x16x32_bf16 v[36:39], v[158:161], v[190:193], v[36:39]
	v_mfma_f32_16x16x32_bf16 v[28:31], v[166:169], v[190:193], v[28:31]
	v_mfma_f32_16x16x32_bf16 v[20:23], v[158:161], v[198:201], v[20:23]
	v_mfma_f32_16x16x32_bf16 v[12:15], v[166:169], v[198:201], v[12:15]
	s_barrier
	s_setprio 0
	s_add_u32 s46, s46, 0x100080
	s_addc_u32 s47, s47, 0
	s_add_i32 s48, s48, s56
	s_mov_b32 m0, s48
	s_nop 0
	global_load_lds_dwordx4 v136, s[46:47]
	s_add_i32 m0, s48, 0x2000
	s_nop 0
	global_load_lds_dwordx4 v140, s[46:47]
	s_waitcnt vmcnt(6)
	s_setprio 1
	s_barrier
	v_mfma_f32_16x16x32_bf16 v[48:51], v[202:205], v[170:173], v[48:51]
	ds_read_b128 v[154:157], v150
	v_mfma_f32_16x16x32_bf16 v[40:43], v[210:213], v[170:173], v[40:43]
	v_mfma_f32_16x16x32_bf16 v[32:35], v[202:205], v[178:181], v[32:35]
	ds_read_b128 v[158:161], v150 offset:1024
	v_mfma_f32_16x16x32_bf16 v[24:27], v[210:213], v[178:181], v[24:27]
	v_mfma_f32_16x16x32_bf16 v[16:19], v[202:205], v[186:189], v[16:19]
	ds_read_b128 v[162:165], v150 offset:2048
	v_mfma_f32_16x16x32_bf16 v[8:11], v[210:213], v[186:189], v[8:11]
	v_mfma_f32_16x16x32_bf16 v[4:7], v[202:205], v[194:197], v[4:7]
	ds_read_b128 v[166:169], v150 offset:3072
	v_mfma_f32_16x16x32_bf16 v[0:3], v[210:213], v[194:197], v[0:3]
	v_mfma_f32_16x16x32_bf16 v[48:51], v[206:209], v[174:177], v[48:51]
	ds_read_b128 v[170:173], v151
	v_mfma_f32_16x16x32_bf16 v[40:43], v[214:217], v[174:177], v[40:43]
	v_mfma_f32_16x16x32_bf16 v[32:35], v[206:209], v[182:185], v[32:35]
	ds_read_b128 v[178:181], v151 offset:2048
	v_mfma_f32_16x16x32_bf16 v[24:27], v[214:217], v[182:185], v[24:27]
	v_mfma_f32_16x16x32_bf16 v[16:19], v[206:209], v[190:193], v[16:19]
	ds_read_b128 v[186:189], v151 offset:4096
	v_mfma_f32_16x16x32_bf16 v[8:11], v[214:217], v[190:193], v[8:11]
	v_mfma_f32_16x16x32_bf16 v[4:7], v[206:209], v[198:201], v[4:7]
	ds_read_b128 v[194:197], v151 offset:6144
	v_mfma_f32_16x16x32_bf16 v[0:3], v[214:217], v[198:201], v[0:3]
	s_barrier
	s_setprio 0
	s_add_i32 s81, s81, 2
	s_add_u32 s36, s36, 0x100
	s_addc_u32 s37, s37, 0
	s_add_u32 s79, s79, 0x100
	s_addc_u32 s80, s80, 0
	s_cmp_gt_u32 s81, 61
	s_cbranch_scc0 .LBB0_457
; __device__ __forceinline__ unsigned cvt_pk_bf16(float lo, float hi) { unsigned r; asm volatile("v_cvt_pk_bf16_f32 %0, %1, %2" : "=v"(r) : "v"(lo), "v"(hi)); return r; }
;     __device__ __forceinline__ void operator()(const f32x4 (&acc)[2][2][4][2], const Unit& u, int wr, int wc, int fr, int fq) const {
;         const int row0 = u.orow + wr * 64 + fr, col0 = u.ocol + wc * 32 + 8 * fq;
; #pragma unroll
;         for (int ai = 0; ai < 2; ++ai)
; #pragma unroll
;             for (int m = 0; m < 4; ++m) { bf16_t* rowp = O + (size_t)(row0 + ai * HALF + m * 16) * ldc + col0;
; #pragma unroll
;                 for (int bj = 0; bj < 2; ++bj) { const f32x4 v0 = acc[ai][bj][m][0], v1 = acc[ai][bj][m][1];
;                     u32x4 w; w.x = cvt_pk_bf16(v0[0], v0[1]); w.y = cvt_pk_bf16(v0[2], v0[3]); w.z = cvt_pk_bf16(v1[0], v1[1]); w.w = cvt_pk_bf16(v1[2], v1[3]);
;                     if (nt) __builtin_nontemporal_store(w, (u32x4*)(rowp + bj * HALF)); else *(u32x4*)(rowp + bj * HALF) = w; } }
	s_waitcnt lgkmcnt(0)
	v_add_u32_e32 v146, s78, v131
	v_ashrrev_i32_e32 v147, 31, v146
	v_add_u32_e32 v154, s77, v149
	v_lshlrev_b64 v[146:147], 13, v[146:147]
	v_ashrrev_i32_e32 v155, 31, v154
	v_lshl_add_u64 v[146:147], s[18:19], 0, v[146:147]
	v_lshl_add_u64 v[146:147], v[154:155], 1, v[146:147]
	v_cvt_pk_bf16_f32 v124, v124, v125
	v_cvt_pk_bf16_f32 v125, v126, v127
	v_cvt_pk_bf16_f32 v126, v120, v121
	v_cvt_pk_bf16_f32 v127, v122, v123
	global_store_dwordx4 v[146:147], v[124:127], off
	v_cvt_pk_bf16_f32 v112, v112, v113
	v_cvt_pk_bf16_f32 v113, v114, v115
	v_cvt_pk_bf16_f32 v114, v104, v105
	v_cvt_pk_bf16_f32 v115, v106, v107
	global_store_dwordx4 v[146:147], v[112:115], off offset:256
	v_cvt_pk_bf16_f32 v104, v116, v117
	v_cvt_pk_bf16_f32 v105, v118, v119
	v_cvt_pk_bf16_f32 v106, v108, v109
	v_add_co_u32_e32 v108, vcc, s68, v146
	s_nop 0
	v_lshl_add_u64 v[112:113], v[146:147], 0, s[10:11]
	v_addc_co_u32_e32 v109, vcc, 0, v147, vcc
	v_cvt_pk_bf16_f32 v107, v110, v111
	global_store_dwordx4 v[108:109], v[104:107], off
	v_cvt_pk_bf16_f32 v96, v96, v97
	v_cvt_pk_bf16_f32 v97, v98, v99
	v_cvt_pk_bf16_f32 v98, v88, v89
	v_cvt_pk_bf16_f32 v99, v90, v91
	global_store_dwordx4 v[112:113], v[96:99], off offset:256
	v_cvt_pk_bf16_f32 v88, v100, v101
	v_cvt_pk_bf16_f32 v89, v102, v103
	v_cvt_pk_bf16_f32 v90, v92, v93
	v_add_co_u32_e32 v92, vcc, s69, v146
	s_nop 0
	v_lshl_add_u64 v[96:97], v[146:147], 0, s[12:13]
	v_addc_co_u32_e32 v93, vcc, 0, v147, vcc
	v_cvt_pk_bf16_f32 v91, v94, v95
	global_store_dwordx4 v[92:93], v[88:91], off
	v_cvt_pk_bf16_f32 v80, v80, v81
	v_cvt_pk_bf16_f32 v81, v82, v83
	v_cvt_pk_bf16_f32 v82, v72, v73
	v_cvt_pk_bf16_f32 v83, v74, v75
	global_store_dwordx4 v[96:97], v[80:83], off offset:256
	v_cvt_pk_bf16_f32 v72, v84, v85
	v_cvt_pk_bf16_f32 v73, v86, v87
	v_cvt_pk_bf16_f32 v74, v76, v77
	v_add_co_u32_e32 v76, vcc, s70, v146
	s_nop 0
	v_lshl_add_u64 v[80:81], v[146:147], 0, s[20:21]
	v_addc_co_u32_e32 v77, vcc, 0, v147, vcc
	v_cvt_pk_bf16_f32 v75, v78, v79
	global_store_dwordx4 v[76:77], v[72:75], off
	v_cvt_pk_bf16_f32 v68, v68, v69
	v_cvt_pk_bf16_f32 v69, v70, v71
	v_cvt_pk_bf16_f32 v70, v64, v65
	v_cvt_pk_bf16_f32 v71, v66, v67
	global_store_dwordx4 v[80:81], v[68:71], off offset:256
	v_cvt_pk_bf16_f32 v60, v60, v61
	v_cvt_pk_bf16_f32 v61, v62, v63
	v_cvt_pk_bf16_f32 v62, v56, v57
	v_add_co_u32_e32 v56, vcc, s71, v146
	v_lshl_add_u64 v[64:65], v[146:147], 0, s[6:7]
	s_nop 0
	v_addc_co_u32_e32 v57, vcc, 0, v147, vcc
	v_cvt_pk_bf16_f32 v63, v58, v59
	global_store_dwordx4 v[56:57], v[60:63], off
	v_cvt_pk_bf16_f32 v48, v48, v49
	v_cvt_pk_bf16_f32 v49, v50, v51
	v_cvt_pk_bf16_f32 v50, v40, v41
	v_cvt_pk_bf16_f32 v51, v42, v43
	global_store_dwordx4 v[64:65], v[48:51], off offset:256
	v_cvt_pk_bf16_f32 v40, v52, v53
	v_cvt_pk_bf16_f32 v41, v54, v55
	v_cvt_pk_bf16_f32 v42, v44, v45
	v_add_co_u32_e32 v44, vcc, s72, v146
	s_nop 0
	v_lshl_add_u64 v[48:49], v[146:147], 0, s[22:23]
	v_addc_co_u32_e32 v45, vcc, 0, v147, vcc
	v_cvt_pk_bf16_f32 v43, v46, v47
	global_store_dwordx4 v[44:45], v[40:43], off
	v_cvt_pk_bf16_f32 v32, v32, v33
	v_cvt_pk_bf16_f32 v33, v34, v35
	v_cvt_pk_bf16_f32 v34, v24, v25
	v_cvt_pk_bf16_f32 v35, v26, v27
	global_store_dwordx4 v[48:49], v[32:35], off offset:256
	v_cvt_pk_bf16_f32 v24, v36, v37
	v_cvt_pk_bf16_f32 v25, v38, v39
	v_cvt_pk_bf16_f32 v26, v28, v29
	v_add_co_u32_e32 v28, vcc, s73, v146
	s_nop 0
	v_lshl_add_u64 v[32:33], v[146:147], 0, s[24:25]
	v_addc_co_u32_e32 v29, vcc, 0, v147, vcc
	v_cvt_pk_bf16_f32 v27, v30, v31
	global_store_dwordx4 v[28:29], v[24:27], off
	v_cvt_pk_bf16_f32 v16, v16, v17
	v_cvt_pk_bf16_f32 v17, v18, v19
	v_cvt_pk_bf16_f32 v18, v8, v9
	v_cvt_pk_bf16_f32 v19, v10, v11
	global_store_dwordx4 v[32:33], v[16:19], off offset:256
	v_cvt_pk_bf16_f32 v8, v20, v21
	v_cvt_pk_bf16_f32 v9, v22, v23
	v_cvt_pk_bf16_f32 v10, v12, v13
	v_add_co_u32_e32 v12, vcc, s74, v146
	s_nop 0
	v_lshl_add_u64 v[16:17], v[146:147], 0, s[26:27]
	v_addc_co_u32_e32 v13, vcc, 0, v147, vcc
	s_and_b64 vcc, exec, s[4:5]
	s_mov_b32 s77, s76
	s_mov_b32 s78, s75
	s_mov_b64 s[46:47], s[30:31]
	s_mov_b64 s[36:37], s[28:29]
	v_cvt_pk_bf16_f32 v11, v14, v15
	global_store_dwordx4 v[12:13], v[8:11], off
	v_cvt_pk_bf16_f32 v4, v4, v5
	v_cvt_pk_bf16_f32 v5, v6, v7
	v_cvt_pk_bf16_f32 v6, v0, v1
	v_cvt_pk_bf16_f32 v7, v2, v3
	global_store_dwordx4 v[16:17], v[4:7], off offset:256
	s_cbranch_vccz .LBB0_450
	s_waitcnt vmcnt(0)
	s_cmpk_gt_u32 s50, 0xff
	s_cbranch_scc1 .LBB0_461
	s_barrier
